# e46: as e45 but the P0 raw/pool_w counter is bumped after the transpose workgroup's three in_w items (acks long back, no stall)
# baseline (speedup 1.0000x reference)
; #define LAS __attribute__((address_space(3)))
; __device__ __forceinline__ f32x4 ld_nt(const float* p) { return __builtin_nontemporal_load((const f32x4*)p); }
; __device__ __forceinline__ void transpose_item(const float* W, int K, int pitch, int ncols, f16* WT, LAS float* scr, int item, int lane) {
;     const int nblk = ncols / 32, kb = item / nblk, nb = item % nblk, k0 = 64 * kb, n0 = 32 * nb;
;     const int kr = lane >> 3, nq = (lane & 7) * 4;
;     f32x4 v[8];
; #pragma unroll
;     for (int i = 0; i < 8; ++i) v[i] = ld_nt(W + (size_t)(k0 + kr + 8 * i) * pitch + n0 + nq);
;     __builtin_amdgcn_sched_barrier(0);
; #pragma unroll
;     for (int i = 0; i < 8; ++i) { LAS float* sp = scr + (kr + 8 * i) * 33 + nq; sp[0] = v[i][0]; sp[1] = v[i][1]; sp[2] = v[i][2]; sp[3] = v[i][3]; }
;     asm volatile("s_waitcnt lgkmcnt(0)" ::: "memory");
;     const int c = lane & 7;
; #pragma unroll
;     for (int j = 0; j < 4; ++j) { const int n = (lane >> 3) + 8 * j; const LAS float* sp = scr + (8 * c) * 33 + n;
;         u32x4 o; o.x = pk_f16(sp[0 * 33], sp[1 * 33]); o.y = pk_f16(sp[2 * 33], sp[3 * 33]); o.z = pk_f16(sp[4 * 33], sp[5 * 33]); o.w = pk_f16(sp[6 * 33], sp[7 * 33]);
;         *(u32x4*)(WT + (size_t)(n0 + n) * K + k0 + 8 * c) = o; }
;     asm volatile("s_waitcnt lgkmcnt(0)" ::: "memory");
; }
; __global__ void __launch_bounds__(NTHREADS, 2) mk_fwd(Args a) {
;     ...
;                    if (b2 < 16) transpose_dispatch(b2 * 8 + wave, a.in[7], a.in[20], a.in[18], a.in[8], a.ws, scr, lane);
;                    for (int it = 80 + 3 * b2; it < 80 + 3 * b2 + 3; ++it) transpose_dispatch(it * 8 + wave, a.in[7], a.in[20], a.in[18], a.in[8], a.ws, scr, lane);
;                    if (b2 >= 16) transpose_dispatch((272 + b2 - 16) * 8 + wave, a.in[7], a.in[20], a.in[18], a.in[8], a.ws, scr, lane); } );
.LBB0_52:
	s_waitcnt vmcnt(0)
	s_barrier
	s_mov_b64 s[98:99], exec
	s_and_b64 exec, exec, s[82:83]
	s_cbranch_execz .Lp0_cnt
	v_mov_b32_e32 v252, 0xe000
	v_mov_b32_e32 v253, 1
	global_atomic_add v252, v253, s[50:51]
.Lp0_cnt:
	s_mov_b64 exec, s[98:99]
	s_cmpk_gt_i32 s16, 0xcf
	s_cbranch_scc0 .LBB0_69
	s_addk_i32 s0, 0x200
	s_cmpk_gt_i32 s0, 0x7f
	s_mov_b64 s[12:13], -1
	s_cbranch_scc0 .LBB0_67
	s_cmpk_gt_u32 s0, 0x27f
	s_cbranch_scc0 .LBB0_64
	s_cmpk_gt_u32 s0, 0xe7f
	s_cbranch_scc0 .LBB0_61
	s_lshl_b32 s1, s0, 5
	s_and_b32 s1, s1, 0x7e0
	s_cmpk_gt_u32 s0, 0x167f
	s_mov_b32 s13, 0
	s_mov_b64 s[14:15], -1
	v_or_b32_e32 v9, s1, v20
	v_or_b32_e32 v8, s1, v21
	v_or_b32_e32 v7, s1, v3
	v_or_b32_e32 v6, s1, v1
	s_cbranch_scc0 .LBB0_58
	s_and_b32 s12, s0, 0x7fffffc0
	s_addk_i32 s12, 0xe980
	s_lshl_b32 s14, s1, 2
	s_add_u32 s14, s40, s14
	v_or_b32_e32 v18, s12, v20
	s_addc_u32 s15, s41, 0
	v_lshlrev_b32_e32 v48, 2, v4
	v_mov_b32_e32 v49, 0
	v_lshl_add_u64 v[40:41], s[14:15], 0, v[48:49]
	v_or_b32_e32 v48, 8, v18
	v_lshlrev_b64 v[12:13], 13, v[48:49]
	v_or_b32_e32 v48, 16, v18
	v_lshlrev_b64 v[24:25], 13, v[48:49]
	v_or_b32_e32 v48, 24, v18
	v_lshlrev_b64 v[26:27], 13, v[48:49]
	v_or_b32_e32 v48, 32, v18
	v_lshlrev_b64 v[32:33], 13, v[48:49]
	v_or_b32_e32 v48, 40, v18
	v_mov_b32_e32 v19, v49
	v_lshlrev_b64 v[34:35], 13, v[48:49]
	v_or_b32_e32 v48, 48, v18
	v_lshlrev_b64 v[10:11], 13, v[18:19]
	v_lshlrev_b64 v[42:43], 13, v[48:49]
	v_or_b32_e32 v48, 56, v18
	v_lshl_add_u64 v[10:11], v[40:41], 0, v[10:11]
	v_lshl_add_u64 v[14:15], v[40:41], 0, v[12:13]
	v_lshl_add_u64 v[24:25], v[40:41], 0, v[24:25]
	v_lshl_add_u64 v[28:29], v[40:41], 0, v[26:27]
	v_lshl_add_u64 v[32:33], v[40:41], 0, v[32:33]
	v_lshl_add_u64 v[36:37], v[40:41], 0, v[34:35]
	v_lshl_add_u64 v[42:43], v[40:41], 0, v[42:43]
	v_lshlrev_b64 v[18:19], 13, v[48:49]
	global_load_dwordx4 v[10:13], v[10:11], off nt
	s_nop 0
	global_load_dwordx4 v[14:17], v[14:15], off nt
	s_nop 0
	global_load_dwordx4 v[24:27], v[24:25], off nt
	s_nop 0
	global_load_dwordx4 v[28:31], v[28:29], off nt
	s_nop 0
	global_load_dwordx4 v[32:35], v[32:33], off nt
	s_nop 0
	global_load_dwordx4 v[36:39], v[36:37], off nt
	v_lshl_add_u64 v[18:19], v[40:41], 0, v[18:19]
	global_load_dwordx4 v[40:43], v[42:43], off nt
	s_nop 0
	global_load_dwordx4 v[44:47], v[18:19], off nt
	s_waitcnt vmcnt(7)
	ds_write2_b32 v22, v10, v11 offset1:1
	ds_write2_b32 v22, v12, v13 offset0:2 offset1:3
	v_add_u32_e32 v10, 0x420, v22
	s_waitcnt vmcnt(6)
	ds_write2_b32 v10, v14, v15 offset1:1
	v_add_u32_e32 v10, 0x428, v22
	ds_write2_b32 v10, v16, v17 offset1:1
	v_add_u32_e32 v10, 0x840, v22
	s_waitcnt vmcnt(5)
	ds_write2_b32 v10, v24, v25 offset1:1
	v_add_u32_e32 v10, 0x848, v22
	ds_write2_b32 v10, v26, v27 offset1:1
	v_add_u32_e32 v10, 0xc60, v22
	s_waitcnt vmcnt(4)
	ds_write2_b32 v10, v28, v29 offset1:1
	v_add_u32_e32 v10, 0xc68, v22
	ds_write2_b32 v10, v30, v31 offset1:1
	v_add_u32_e32 v10, 0x1080, v22
	s_waitcnt vmcnt(3)
	ds_write2_b32 v10, v32, v33 offset1:1
	v_add_u32_e32 v10, 0x1088, v22
	ds_write2_b32 v10, v34, v35 offset1:1
	v_add_u32_e32 v10, 0x14a0, v22
	s_waitcnt vmcnt(2)
	ds_write2_b32 v10, v36, v37 offset1:1
	v_add_u32_e32 v10, 0x14a8, v22
	ds_write2_b32 v10, v38, v39 offset1:1
	v_add_u32_e32 v10, 0x18c0, v22
	s_waitcnt vmcnt(1)
	ds_write2_b32 v10, v40, v41 offset1:1
	v_add_u32_e32 v10, 0x18c8, v22
	ds_write2_b32 v10, v42, v43 offset1:1
	v_add_u32_e32 v10, 0x1ce0, v22
	s_waitcnt vmcnt(0)
	ds_write2_b32 v10, v44, v45 offset1:1
	v_add_u32_e32 v10, 0x1ce8, v22
	ds_write2_b32 v10, v46, v47 offset1:1
	s_waitcnt lgkmcnt(0)
	ds_read2_b32 v[14:15], v5 offset0:33 offset1:41
	ds_read2_b32 v[16:17], v5 offset1:8
	ds_read2_b32 v[18:19], v5 offset0:66 offset1:74
	ds_read2_b32 v[24:25], v5 offset0:99 offset1:107
	ds_read2_b32 v[26:27], v5 offset0:132 offset1:140
	ds_read2_b32 v[28:29], v5 offset0:165 offset1:173
	ds_read2_b32 v[30:31], v5 offset0:198 offset1:206
	ds_read2_b32 v[32:33], v5 offset0:231 offset1:239
	s_lshl_b64 s[12:13], s[12:13], 1
	s_add_u32 s10, s10, s12
	s_addc_u32 s11, s11, s13
	v_lshlrev_b32_e32 v48, 1, v2
	v_lshl_add_u64 v[34:35], s[10:11], 0, v[48:49]
	v_lshlrev_b32_e32 v48, 11, v9
	s_waitcnt lgkmcnt(6)
	v_cvt_pk_bf16_f32 v10, v16, v14
	s_waitcnt lgkmcnt(4)
	v_cvt_pk_bf16_f32 v11, v18, v24
	s_waitcnt lgkmcnt(2)
	v_cvt_pk_bf16_f32 v12, v26, v28
	s_waitcnt lgkmcnt(0)
	v_cvt_pk_bf16_f32 v13, v30, v32
	v_lshl_add_u64 v[36:37], v[34:35], 0, v[48:49]
	global_store_dwordx4 v[36:37], v[10:13], off
	v_lshlrev_b32_e32 v48, 11, v8
	s_mov_b64 s[14:15], 0
	v_cvt_pk_bf16_f32 v10, v17, v15
	v_cvt_pk_bf16_f32 v11, v19, v25
	v_cvt_pk_bf16_f32 v12, v27, v29
	v_cvt_pk_bf16_f32 v13, v31, v33
	ds_read2_b32 v[16:17], v5 offset0:49 offset1:57
	ds_read2_b32 v[18:19], v5 offset0:16 offset1:24
	ds_read2_b32 v[24:25], v5 offset0:82 offset1:90
	ds_read2_b32 v[26:27], v5 offset0:115 offset1:123
	ds_read2_b32 v[28:29], v5 offset0:148 offset1:156
	ds_read2_b32 v[30:31], v5 offset0:181 offset1:189
	ds_read2_b32 v[32:33], v5 offset0:214 offset1:222
	ds_read2_b32 v[36:37], v5 offset0:247 offset1:255
	v_lshl_add_u64 v[14:15], v[34:35], 0, v[48:49]
	v_lshlrev_b32_e32 v48, 11, v7
	global_store_dwordx4 v[14:15], v[10:13], off
	v_lshl_add_u64 v[14:15], v[34:35], 0, v[48:49]
	v_lshlrev_b32_e32 v48, 11, v6
	s_waitcnt lgkmcnt(6)
	v_cvt_pk_bf16_f32 v10, v18, v16
	s_waitcnt lgkmcnt(4)
	v_cvt_pk_bf16_f32 v11, v24, v26
	s_waitcnt lgkmcnt(2)
	v_cvt_pk_bf16_f32 v12, v28, v30
	s_waitcnt lgkmcnt(0)
	v_cvt_pk_bf16_f32 v13, v32, v36
	global_store_dwordx4 v[14:15], v[10:13], off
	v_lshl_add_u64 v[14:15], v[34:35], 0, v[48:49]
	s_nop 0
	v_cvt_pk_bf16_f32 v10, v19, v17
	v_cvt_pk_bf16_f32 v11, v25, v27
	v_cvt_pk_bf16_f32 v12, v29, v31
	v_cvt_pk_bf16_f32 v13, v33, v37
	global_store_dwordx4 v[14:15], v[10:13], off
	s_waitcnt lgkmcnt(0)
